# P2 meta-row skinny path: all 55 operand loads issued up front (4 tuples in AGPRs) instead of a 6-deep load/MFMA pipeline
# baseline (speedup 1.0000x reference)
; __global__ void __launch_bounds__(NT, 2) hymba_fwd(Args args) {
;     ...
;             const bf16* ap = ACT + (size_t)(MROW0 + fr) * DFF + wave * 352 + fq * 8;
;             const bf16* bp = W1O + (size_t)(64 * bid + fr) * DFF + wave * 352 + fq * 8;
;             bf16x8 av[11];
; #pragma unroll
;             for (int ks = 0; ks < 11; ++ks) av[ks] = *(const bf16x8*)(ap + ks * 32);
; #pragma unroll
;             for (int tp = 0; tp < 2; ++tp) { bf16x8 bv[2][11];
; #pragma unroll
;                 for (int t = 0; t < 2; ++t)
; #pragma unroll
;                     for (int ks = 0; ks < 11; ++ks) bv[t][ks] = *(const bf16x8*)(bp + (size_t)(2 * tp + t) * 16 * DFF + ks * 32);
; #pragma unroll
;                 for (int t = 0; t < 2; ++t)
; #pragma unroll
;                     for (int ks = 0; ks < 11; ++ks) acc[2 * tp + t] = __builtin_amdgcn_mfma_f32_16x16x32_bf16(av[ks], bv[t][ks], acc[2 * tp + t], 0, 0, 0); }
.LBB0_378:
.LBB0_379:
	v_and_b32_e32 v108, 15, v179
	s_waitcnt vmcnt(31)
	v_mul_u32_u24_e32 v0, 0xb00, v108
	v_readlane_b32 s18, v237, 6
	v_lshlrev_b32_e32 v0, 1, v0
	s_mov_b32 s5, 0
	s_waitcnt vmcnt(30)
	v_mov_b32_e32 v1, 0
	s_mul_i32 s4, s18, 0x160
	s_waitcnt vmcnt(28)
	v_lshl_add_u64 v[2:3], s[82:83], 0, v[0:1]
	s_lshl_b64 s[6:7], s[4:5], 1
	v_lshl_add_u64 v[2:3], v[2:3], 0, s[6:7]
	v_and_b32_e32 v0, 48, v178
	s_lshl_b32 s4, s68, 6
	s_waitcnt vmcnt(12)
	v_lshl_add_u64 v[18:19], v[2:3], 0, v[0:1]
	v_or_b32_e32 v4, s4, v108
	s_movk_i32 s5, 0x1600
	v_mov_b64_e32 v[2:3], s[12:13]
	v_mad_i64_i32 v[2:3], s[8:9], v4, s5, v[2:3]
	s_mov_b32 s5, 0x5800000
	v_add_co_u32_e32 v10, vcc, s5, v18
	v_lshl_add_u64 v[2:3], v[2:3], 0, s[6:7]
	s_nop 0
	v_addc_co_u32_e32 v11, vcc, 0, v19, vcc
	v_lshl_add_u64 v[78:79], v[2:3], 0, v[0:1]
	s_mov_b32 s5, 0x16000
	v_add_co_u32_e32 v74, vcc, s5, v78
	s_mov_b32 s5, 0x2c000
	s_nop 0
	v_addc_co_u32_e32 v75, vcc, 0, v79, vcc
	v_add_co_u32_e32 v76, vcc, s5, v78
	s_mov_b64 s[6:7], 0x5800000
	s_nop 0
	v_addc_co_u32_e32 v77, vcc, 0, v79, vcc
	v_lshl_add_u64 v[80:81], v[18:19], 0, s[6:7]
	s_mov_b32 s5, 0x42000
	v_add_co_u32_e32 v106, vcc, s5, v78
	s_nop 1
	v_addc_co_u32_e32 v107, vcc, 0, v79, vcc
	global_load_dwordx4 v[18:21], v[80:81], off
	global_load_dwordx4 v[22:25], v[78:79], off
	global_load_dwordx4 v[26:29], v[74:75], off
	global_load_dwordx4 v[30:33], v[76:77], off
	global_load_dwordx4 v[34:37], v[106:107], off
	global_load_dwordx4 v[38:41], v[80:81], off offset:64
	global_load_dwordx4 v[42:45], v[78:79], off offset:64
	global_load_dwordx4 v[46:49], v[74:75], off offset:64
	global_load_dwordx4 v[50:53], v[76:77], off offset:64
	global_load_dwordx4 v[54:57], v[106:107], off offset:64
	global_load_dwordx4 v[58:61], v[80:81], off offset:128
	global_load_dwordx4 v[62:65], v[78:79], off offset:128
	global_load_dwordx4 v[66:69], v[74:75], off offset:128
	global_load_dwordx4 v[70:73], v[76:77], off offset:128
	global_load_dwordx4 v[82:85], v[106:107], off offset:128
	global_load_dwordx4 v[86:89], v[80:81], off offset:192
	global_load_dwordx4 v[90:93], v[78:79], off offset:192
	global_load_dwordx4 v[94:97], v[74:75], off offset:192
	global_load_dwordx4 v[98:101], v[76:77], off offset:192
	global_load_dwordx4 v[102:105], v[106:107], off offset:192
	global_load_dwordx4 v[110:113], v[80:81], off offset:256
	global_load_dwordx4 v[114:117], v[78:79], off offset:256
	global_load_dwordx4 v[118:121], v[74:75], off offset:256
	global_load_dwordx4 v[122:125], v[76:77], off offset:256
	global_load_dwordx4 v[126:129], v[106:107], off offset:256
	global_load_dwordx4 v[130:133], v[80:81], off offset:320
	global_load_dwordx4 v[134:137], v[78:79], off offset:320
	global_load_dwordx4 v[138:141], v[74:75], off offset:320
	global_load_dwordx4 v[142:145], v[76:77], off offset:320
	global_load_dwordx4 v[146:149], v[106:107], off offset:320
	global_load_dwordx4 v[150:153], v[80:81], off offset:384
	global_load_dwordx4 v[154:157], v[78:79], off offset:384
	global_load_dwordx4 v[158:161], v[74:75], off offset:384
	global_load_dwordx4 v[162:165], v[76:77], off offset:384
	global_load_dwordx4 v[166:169], v[106:107], off offset:384
	global_load_dwordx4 v[170:173], v[80:81], off offset:448
	global_load_dwordx4 v[174:177], v[78:79], off offset:448
	global_load_dwordx4 v[180:183], v[74:75], off offset:448
	global_load_dwordx4 v[184:187], v[76:77], off offset:448
	global_load_dwordx4 v[188:191], v[106:107], off offset:448
	global_load_dwordx4 v[192:195], v[80:81], off offset:512
	global_load_dwordx4 v[196:199], v[78:79], off offset:512
	global_load_dwordx4 v[200:203], v[74:75], off offset:512
	global_load_dwordx4 v[204:207], v[76:77], off offset:512
	global_load_dwordx4 v[208:211], v[106:107], off offset:512
	global_load_dwordx4 v[212:215], v[80:81], off offset:576
	global_load_dwordx4 v[216:219], v[78:79], off offset:576
	global_load_dwordx4 v[220:223], v[74:75], off offset:576
	global_load_dwordx4 v[224:227], v[76:77], off offset:576
	global_load_dwordx4 v[228:231], v[106:107], off offset:576
	global_load_dwordx4 v[232:235], v[80:81], off offset:640
	global_load_dwordx4 a[0:3], v[78:79], off offset:640
	global_load_dwordx4 a[4:7], v[74:75], off offset:640
	global_load_dwordx4 a[8:11], v[76:77], off offset:640
	global_load_dwordx4 a[12:15], v[106:107], off offset:640
	v_lshlrev_b32_e32 v0, 6, v178
	v_and_b32_e32 v0, 0xc00, v0
	s_movk_i32 s6, 0x7fff
	s_mov_b32 s7, 0xffff0000
	v_add_co_u32_e32 v78, vcc, s5, v78
	v_addc_co_u32_e32 v79, vcc, 0, v79, vcc
	s_waitcnt vmcnt(50)
	v_mfma_f32_16x16x32_bf16 v[6:9], v[18:21], v[22:25], 0
	v_mfma_f32_16x16x32_bf16 v[10:13], v[18:21], v[26:29], 0
	v_mfma_f32_16x16x32_bf16 v[14:17], v[18:21], v[30:33], 0
	v_mfma_f32_16x16x32_bf16 v[2:5], v[18:21], v[34:37], 0
	s_waitcnt vmcnt(45)
	v_mfma_f32_16x16x32_bf16 v[6:9], v[38:41], v[42:45], v[6:9]
	v_mfma_f32_16x16x32_bf16 v[10:13], v[38:41], v[46:49], v[10:13]
	v_mfma_f32_16x16x32_bf16 v[14:17], v[38:41], v[50:53], v[14:17]
	v_mfma_f32_16x16x32_bf16 v[2:5], v[38:41], v[54:57], v[2:5]
	s_waitcnt vmcnt(40)
	v_mfma_f32_16x16x32_bf16 v[6:9], v[58:61], v[62:65], v[6:9]
	v_mfma_f32_16x16x32_bf16 v[10:13], v[58:61], v[66:69], v[10:13]
	v_mfma_f32_16x16x32_bf16 v[14:17], v[58:61], v[70:73], v[14:17]
	v_mfma_f32_16x16x32_bf16 v[2:5], v[58:61], v[82:85], v[2:5]
	s_waitcnt vmcnt(35)
	v_mfma_f32_16x16x32_bf16 v[6:9], v[86:89], v[90:93], v[6:9]
	v_mfma_f32_16x16x32_bf16 v[10:13], v[86:89], v[94:97], v[10:13]
	v_mfma_f32_16x16x32_bf16 v[14:17], v[86:89], v[98:101], v[14:17]
	v_mfma_f32_16x16x32_bf16 v[2:5], v[86:89], v[102:105], v[2:5]
	s_waitcnt vmcnt(30)
; #define LAS __attribute__((address_space(3)))
; __device__ __forceinline__ unsigned pk2(float lo, float hi) { return f2bf(lo) | (f2bf(hi) << 16); }
; __global__ void __launch_bounds__(NT, 2) hymba_fwd(Args args) {
;     ...
;             for (int tp = 0; tp < 2; ++tp) { bf16x8 bv[2][11];
; #pragma unroll
;                 for (int t = 0; t < 2; ++t)
; #pragma unroll
;                     for (int ks = 0; ks < 11; ++ks) bv[t][ks] = *(const bf16x8*)(bp + (size_t)(2 * tp + t) * 16 * DFF + ks * 32);
; #pragma unroll
;                 for (int t = 0; t < 2; ++t)
; #pragma unroll
;                     for (int ks = 0; ks < 11; ++ks) acc[2 * tp + t] = __builtin_amdgcn_mfma_f32_16x16x32_bf16(av[ks], bv[t][ks], acc[2 * tp + t], 0, 0, 0); }
;             LAS float* part = (LAS float*)(lds + wave * 4096);
; #pragma unroll
;             for (int t = 0; t < 4; ++t)
; #pragma unroll
;                 for (int j = 0; j < 4; ++j) part[(fq * 4 + j) * 64 + t * 16 + fr] = acc[t][j];
;             __syncthreads();
;             const int row = tid >> 5, c2 = (tid & 31) * 2; float hv[2]; float sq = 0.f;
; #pragma unroll
;             for (int e = 0; e < 2; ++e) { float sm = 0.f;
; #pragma unroll
;                 for (int w = 0; w < 8; ++w) sm += ((LAS float*)(lds + w * 4096))[row * 64 + c2 + e];
;                 hv[e] = meta[(size_t)row * D + 64 * bid + c2 + e] + 0.5f * sm; sq += hv[e] * hv[e]; }
;             *(unsigned*)(ABUF + (size_t)(MROW0 + row) * D + 64 * bid + c2) = pk2(hv[0], hv[1]);
; #pragma unroll
;             for (int of = 1; of < 32; of <<= 1) sq += __shfl_xor(sq, of);
;             if ((tid & 31) == 0) SSQ1[(size_t)(MROW0 + row) * 16 + bid] = sq;
	v_mfma_f32_16x16x32_bf16 v[6:9], v[110:113], v[114:117], v[6:9]
	v_mfma_f32_16x16x32_bf16 v[10:13], v[110:113], v[118:121], v[10:13]
	v_mfma_f32_16x16x32_bf16 v[14:17], v[110:113], v[122:125], v[14:17]
	v_mfma_f32_16x16x32_bf16 v[2:5], v[110:113], v[126:129], v[2:5]
	s_waitcnt vmcnt(25)
	v_mfma_f32_16x16x32_bf16 v[6:9], v[130:133], v[134:137], v[6:9]
	v_mfma_f32_16x16x32_bf16 v[10:13], v[130:133], v[138:141], v[10:13]
	v_mfma_f32_16x16x32_bf16 v[14:17], v[130:133], v[142:145], v[14:17]
	v_mfma_f32_16x16x32_bf16 v[2:5], v[130:133], v[146:149], v[2:5]
	s_waitcnt vmcnt(20)
	v_mfma_f32_16x16x32_bf16 v[6:9], v[150:153], v[154:157], v[6:9]
	v_mfma_f32_16x16x32_bf16 v[10:13], v[150:153], v[158:161], v[10:13]
	v_mfma_f32_16x16x32_bf16 v[14:17], v[150:153], v[162:165], v[14:17]
	v_mfma_f32_16x16x32_bf16 v[2:5], v[150:153], v[166:169], v[2:5]
	s_waitcnt vmcnt(15)
	v_mfma_f32_16x16x32_bf16 v[6:9], v[170:173], v[174:177], v[6:9]
	v_mfma_f32_16x16x32_bf16 v[10:13], v[170:173], v[180:183], v[10:13]
	v_mfma_f32_16x16x32_bf16 v[14:17], v[170:173], v[184:187], v[14:17]
	v_mfma_f32_16x16x32_bf16 v[2:5], v[170:173], v[188:191], v[2:5]
	s_waitcnt vmcnt(10)
	v_mfma_f32_16x16x32_bf16 v[6:9], v[192:195], v[196:199], v[6:9]
	v_mfma_f32_16x16x32_bf16 v[10:13], v[192:195], v[200:203], v[10:13]
	v_mfma_f32_16x16x32_bf16 v[14:17], v[192:195], v[204:207], v[14:17]
	v_mfma_f32_16x16x32_bf16 v[2:5], v[192:195], v[208:211], v[2:5]
	s_waitcnt vmcnt(5)
	v_mfma_f32_16x16x32_bf16 v[6:9], v[212:215], v[216:219], v[6:9]
	v_mfma_f32_16x16x32_bf16 v[10:13], v[212:215], v[220:223], v[10:13]
	v_mfma_f32_16x16x32_bf16 v[14:17], v[212:215], v[224:227], v[14:17]
	v_mfma_f32_16x16x32_bf16 v[2:5], v[212:215], v[228:231], v[2:5]
	s_waitcnt vmcnt(0)
	v_mfma_f32_16x16x32_bf16 v[6:9], v[232:235], a[0:3], v[6:9]
	v_mfma_f32_16x16x32_bf16 v[10:13], v[232:235], a[4:7], v[10:13]
	v_mfma_f32_16x16x32_bf16 v[14:17], v[232:235], a[8:11], v[14:17]
	v_mfma_f32_16x16x32_bf16 v[2:5], v[232:235], a[12:15], v[2:5]
	s_nop 7
	s_lshl_b32 s5, s18, 12
	s_add_i32 s5, s5, 0
	v_lshlrev_b32_e32 v22, 2, v108
	v_add3_u32 v0, s5, v0, v22
	ds_write2_b32 v0, v6, v10 offset1:16
	ds_write2_b32 v0, v7, v11 offset0:64 offset1:80
	ds_write2_b32 v0, v8, v12 offset0:128 offset1:144
	ds_write2_b32 v0, v9, v13 offset0:192 offset1:208
	v_and_b32_e32 v22, 31, v179
	s_ashr_i32 s5, s4, 31
	v_mov_b32_e32 v23, 1
	s_nop 1
	ds_write2_b32 v0, v14, v2 offset0:32 offset1:48
	ds_write2_b32 v0, v15, v3 offset0:96 offset1:112
	ds_write2_b32 v0, v16, v4 offset0:160 offset1:176
	ds_write2_b32 v0, v17, v5 offset0:224 offset1:240
	v_lshrrev_b32_e32 v2, 5, v179
	v_lshlrev_b32_e32 v0, 12, v2
	v_lshl_add_u64 v[6:7], s[14:15], 0, v[0:1]
	v_lshlrev_b32_e32 v4, 3, v22
	v_lshl_add_u64 v[6:7], s[4:5], 2, v[6:7]
	v_mov_b32_e32 v5, v1
	v_lshl_add_u64 v[6:7], v[6:7], 0, v[4:5]
	s_waitcnt lgkmcnt(0)
	s_barrier
	global_load_dwordx2 v[20:21], v[6:7], off
	v_mbcnt_lo_u32_b32 v0, -1, 0
	v_lshlrev_b32_e32 v5, 8, v2
	v_mbcnt_hi_u32_b32 v0, -1, v0
	v_add3_u32 v16, 0, v5, v4
	v_and_b32_e32 v4, 64, v0
	v_xor_b32_e32 v5, 1, v0
	v_add_u32_e32 v27, 64, v4
	v_xor_b32_e32 v6, 2, v0
	v_cmp_lt_i32_e32 vcc, v5, v27
	v_xor_b32_e32 v24, 4, v0
	v_xor_b32_e32 v25, 8, v0
	v_cndmask_b32_e32 v8, v0, v5, vcc
	v_cmp_lt_i32_e32 vcc, v6, v27
	v_lshlrev_b32_e32 v29, 2, v8
	v_xor_b32_e32 v26, 16, v0
	v_cndmask_b32_e32 v28, v0, v6, vcc
	ds_read2st64_b64 v[4:7], v16 offset1:8
	ds_read2st64_b64 v[8:11], v16 offset0:16 offset1:24
	ds_read2st64_b64 v[12:15], v16 offset0:32 offset1:40
	ds_read2st64_b64 v[16:19], v16 offset0:48 offset1:56
	v_cmp_lt_i32_e32 vcc, v24, v27
	v_or_b32_e32 v3, 0x4000, v2
	s_waitcnt lgkmcnt(3)
	v_pk_add_f32 v[4:5], v[4:5], 0 op_sel_hi:[1,0]
	s_nop 0
	v_pk_add_f32 v[4:5], v[4:5], v[6:7]
	s_waitcnt lgkmcnt(2)
	v_pk_add_f32 v[4:5], v[4:5], v[8:9]
	v_cndmask_b32_e32 v8, v0, v24, vcc
	v_pk_add_f32 v[4:5], v[4:5], v[10:11]
	v_lshlrev_b32_e32 v10, 2, v28
	s_waitcnt lgkmcnt(1)
	v_pk_add_f32 v[4:5], v[4:5], v[12:13]
	v_lshlrev_b32_e32 v8, 2, v8
	v_pk_add_f32 v[4:5], v[4:5], v[14:15]
	v_cmp_lt_i32_e32 vcc, v25, v27
	s_waitcnt lgkmcnt(0)
	v_pk_add_f32 v[4:5], v[4:5], v[16:17]
	s_nop 0
	v_pk_add_f32 v[4:5], v[4:5], v[18:19]
	v_cndmask_b32_e32 v9, v0, v25, vcc
	v_lshlrev_b32_e32 v9, 2, v9
	v_cmp_lt_i32_e32 vcc, v26, v27
	s_waitcnt vmcnt(0)
	v_pk_fma_f32 v[4:5], v[4:5], 0.5, v[20:21] op_sel_hi:[1,0,1]
	s_nop 0
	v_pk_mul_f32 v[6:7], v[4:5], v[4:5]
	v_and_b32_sdwa v12, v4, v23 dst_sel:DWORD dst_unused:UNUSED_PAD src0_sel:WORD_1 src1_sel:DWORD
	v_add_f32_e32 v6, v6, v7
	ds_bpermute_b32 v7, v29, v6
	v_add3_u32 v4, v4, v12, s6
	v_lshrrev_b32_e32 v4, 16, v4
	s_waitcnt lgkmcnt(0)
	v_add_f32_e32 v6, v6, v7
	ds_bpermute_b32 v7, v10, v6
	v_cndmask_b32_e32 v10, v0, v26, vcc
	v_lshlrev_b32_e32 v0, 11, v3
	v_cmp_eq_u32_e32 vcc, 0, v22
	s_waitcnt lgkmcnt(0)
	v_add_f32_e32 v11, v6, v7
	ds_bpermute_b32 v8, v8, v11
	v_lshl_add_u64 v[6:7], s[80:81], 0, v[0:1]
	v_and_b32_sdwa v0, v5, v23 dst_sel:DWORD dst_unused:UNUSED_PAD src0_sel:WORD_1 src1_sel:DWORD
	v_add3_u32 v0, v5, v0, s6
	v_lshl_add_u64 v[6:7], s[4:5], 1, v[6:7]
	s_waitcnt lgkmcnt(0)
	v_add_f32_e32 v8, v11, v8
	ds_bpermute_b32 v9, v9, v8
	v_and_or_b32 v11, v0, s7, v4
	v_lshlrev_b32_e32 v0, 2, v10
	s_waitcnt lgkmcnt(0)
	v_add_f32_e32 v4, v8, v9
	ds_bpermute_b32 v5, v0, v4
	v_lshlrev_b32_e32 v0, 2, v22
	v_lshl_add_u64 v[6:7], v[6:7], 0, v[0:1]
	global_store_dword v[6:7], v11, off
	s_and_saveexec_b64 s[4:5], vcc
	s_cbranch_execz .LBB0_381
	v_lshlrev_b32_e32 v0, 6, v3
	v_lshl_add_u64 v[0:1], s[10:11], 0, v[0:1]
	s_ashr_i32 s69, s68, 31
	s_waitcnt lgkmcnt(0)
	v_add_f32_e32 v4, v4, v5
	v_lshl_add_u64 v[0:1], s[68:69], 2, v[0:1]
	global_store_dword v[0:1], v4, off

; __global__ void __launch_bounds__(NT, 2) hymba_fwd(Args args) {
	.amdhsa_kernel _Z9hymba_fwd4Args
		.amdhsa_group_segment_fixed_size 0
		.amdhsa_private_segment_fixed_size 0
		.amdhsa_kernarg_size 408
		.amdhsa_user_sgpr_count 2
		.amdhsa_user_sgpr_dispatch_ptr 0
		.amdhsa_user_sgpr_queue_ptr 0
		.amdhsa_user_sgpr_kernarg_segment_ptr 1
		.amdhsa_user_sgpr_dispatch_id 0
		.amdhsa_user_sgpr_kernarg_preload_length 0
		.amdhsa_user_sgpr_kernarg_preload_offset 0
		.amdhsa_user_sgpr_private_segment_size 0
		.amdhsa_uses_dynamic_stack 0
		.amdhsa_enable_private_segment 0
		.amdhsa_system_sgpr_workgroup_id_x 1
		.amdhsa_system_sgpr_workgroup_id_y 0
		.amdhsa_system_sgpr_workgroup_id_z 0
		.amdhsa_system_sgpr_workgroup_info 0
		.amdhsa_system_vgpr_workitem_id 2
		.amdhsa_next_free_vgpr 256
		.amdhsa_next_free_sgpr 102
		.amdhsa_accum_offset 240
		.amdhsa_reserve_vcc 1
		.amdhsa_float_round_mode_32 0
		.amdhsa_float_round_mode_16_64 0
		.amdhsa_float_denorm_mode_32 3
		.amdhsa_float_denorm_mode_16_64 3
		.amdhsa_dx10_clamp 1
		.amdhsa_ieee_mode 1
		.amdhsa_fp16_overflow 0
		.amdhsa_tg_split 0
		.amdhsa_exception_fp_ieee_invalid_op 0
		.amdhsa_exception_fp_denorm_src 0
		.amdhsa_exception_fp_ieee_div_zero 0
		.amdhsa_exception_fp_ieee_overflow 0
		.amdhsa_exception_fp_ieee_underflow 0
		.amdhsa_exception_fp_ieee_inexact 0
		.amdhsa_exception_int_div_zero 0
	.end_amdhsa_kernel

; __global__ void __launch_bounds__(NT, 2) hymba_fwd(Args args) {
amdhsa.kernels:
  - .agpr_count:     16
    .args:
      - .offset:         0
        .size:           152
        .value_kind:     by_value
      - .offset:         152
        .size:           4
        .value_kind:     hidden_block_count_x
      - .offset:         156
        .size:           4
        .value_kind:     hidden_block_count_y
      - .offset:         160
        .size:           4
        .value_kind:     hidden_block_count_z
      - .offset:         164
        .size:           2
        .value_kind:     hidden_group_size_x
      - .offset:         166
        .size:           2
        .value_kind:     hidden_group_size_y
      - .offset:         168
        .size:           2
        .value_kind:     hidden_group_size_z
      - .offset:         170
        .size:           2
        .value_kind:     hidden_remainder_x
      - .offset:         172
        .size:           2
        .value_kind:     hidden_remainder_y
      - .offset:         174
        .size:           2
        .value_kind:     hidden_remainder_z
      - .offset:         192
        .size:           8
        .value_kind:     hidden_global_offset_x
      - .offset:         200
        .size:           8
        .value_kind:     hidden_global_offset_y
      - .offset:         208
        .size:           8
        .value_kind:     hidden_global_offset_z
      - .offset:         216
        .size:           2
        .value_kind:     hidden_grid_dims
      - .offset:         240
        .size:           8
        .value_kind:     hidden_multigrid_sync_arg
      - .offset:         272
        .size:           4
        .value_kind:     hidden_dynamic_lds_size
    .group_segment_fixed_size: 0
    .kernarg_segment_align: 8
    .kernarg_segment_size: 408
    .language:       OpenCL C
    .language_version:
      - 2
      - 0
    .max_flat_workgroup_size: 512
    .name:           _Z9hymba_fwd4Args
    .private_segment_fixed_size: 0
    .sgpr_count:     108
    .sgpr_spill_count: 133
    .symbol:         _Z9hymba_fwd4Args.kd
    .uniform_work_group_size: 1
    .uses_dynamic_stack: false
    .vgpr_count:     238
    .vgpr_spill_count: 0
    .wavefront_size: 64
